# attn64 loop back-edge rotation: counters, exit test and next DMA address math moved before the pair barrier
# speedup vs baseline: 1.0006x; 1.0006x over previous
.Latt64_skip_h2:
	s_addk_i32 s80, 0x4000
	v_add_u32_e32 v214, 0x8000, v214
	s_add_i32 s92, s92, 2
	s_add_i32 s14, s14, 0x8000
	s_add_i32 s13, s13, 2
	v_add_u32_e32 v215, 0x8000, v215
	s_add_i32 s81, s81, 2
	s_add_i32 s15, s15, 0x8000
	s_add_i32 s12, s12, 2
	s_and_b64 vcc, exec, s[68:69]
	s_cbranch_vccnz .Latt64_exit_bar
	s_mov_b32 s10, s6
	s_mov_b32 s84, s83
	s_add_i32 s6, s84, 1
	s_cmp_ge_u32 s6, s50
	s_cbranch_scc1 .Latt64_bar_nodma
	s_mul_hi_u32 s17, s12, 0xcccccccd
	s_lshr_b32 s17, s17, 2
	s_mul_i32 s17, s17, 0x14000
	s_min_i32 s6, s6, s49
	s_sub_i32 s17, s15, s17
	s_lshl_b64 s[18:19], s[6:7], 17
	s_add_u32 s20, s52, s18
	s_addc_u32 s21, s53, s19
	s_add_u32 s18, s66, s18
	s_addc_u32 s19, s67, s19
	s_add_u32 s24, s20, 0x10000
	s_addc_u32 s25, s21, 0
	s_add_i32 s23, s17, 0x2000
	s_add_i32 s22, s80, 0x2000
	s_and_b32 s22, s22, 0x6000
	s_add_i32 s22, s22, s11
	s_waitcnt vmcnt(0) lgkmcnt(0)
	s_barrier
	s_mov_b32 m0, s17
	s_nop 0
	global_load_lds_dwordx4 v194, s[20:21]
	s_mov_b32 m0, s23
	s_nop 0
	global_load_lds_dwordx4 v194, s[24:25]
	s_mov_b32 m0, s22
	s_nop 0
	global_load_lds_dwordx4 v195, s[18:19]
	s_branch .LBB0_938
.Latt64_bar_nodma:
	s_waitcnt vmcnt(0) lgkmcnt(0)
	s_barrier
	s_branch .LBB0_938
